# v038_poolfirst
# speedup vs baseline: 1.0210x; 1.0210x over previous
; __device__ __forceinline__ void phase_mixers(const Params& p, int cidx, int layer) {
;     ...
;     const int it = s_item;
;     if (it >= N_SSM + N_POOL + N_ATT + n_cv) break;
;     if (it < N_SSM) ssm_item(p, layer, it & 127, tidx);
;     else if (it < N_SSM + N_POOL) pool_block_item(p, layer, (it - N_SSM) & 255, tidx);
;     else if (it < N_SSM + N_POOL + N_ATT) attn_wave_item(p, ((it - N_SSM - N_POOL) & 511) * 8 + wid, tidx);
;     else cv_item_B(p, (it - N_SSM - N_POOL - N_ATT) % CV_B, tidx);
.LBB0_77:
	s_or_b64 exec, exec, s[6:7]
	s_waitcnt lgkmcnt(0)
	s_barrier
	ds_read_b32 v0, v163 offset:20
	s_mov_b64 s[6:7], -1
	s_waitcnt lgkmcnt(0)
	v_cmp_le_i32_e32 vcc, s65, v0
	v_readfirstlane_b32 s64, v0
	s_cbranch_vccnz .LBB0_72
	v_ashrrev_i32_e32 v97, 6, v164
	s_cmp_lt_u32 s64, 0x180
	s_cbranch_scc0 .Lpf_done
	s_cmp_lt_u32 s64, 0x100
	s_cbranch_scc1 .Lpf_pool
	s_sub_u32 s64, s64, 0x100
	s_branch .Lpf_done
